# K-loop loop-edge edit: back-edge bookkeeping (pointer advance + exit compare) moved into the last MFMA block's shadow
# baseline (speedup 1.0000x reference)
; #define PG8_STAGE(bufoff, gbase, voff) do { _Pragma("unroll") for (int _i = 0; _i < 2; ++_i) \
;         __builtin_amdgcn_global_load_lds((const unsigned*)((const char*)(gbase) + (voff)[_i]), (PG8_LAS unsigned*)(lds + (bufoff) + ldsw + _i * 8192), 16, 0, 0); } while (0)
; #define PG8_LDA(dst, b, h) do { _Pragma("unroll") for (int m = 0; m < 4; ++m) _Pragma("unroll") for (int k = 0; k < 2; ++k) dst[m][k] = *(const PG8_LAS bf16x8*)(lds + PG8_SA(b, h) + aoff + m * 2048 + k * 1024); } while (0)
; #define PG8_LDB(dst, b, h) do { _Pragma("unroll") for (int n = 0; n < 2; ++n) _Pragma("unroll") for (int k = 0; k < 2; ++k) dst[n][k] = *(const PG8_LAS bf16x8*)(lds + PG8_SB(b, h) + boff + n * 2048 + k * 1024); } while (0)
; #define PG8_MMA(ai, bj, At, Bt) do { __builtin_amdgcn_s_setprio(1); _Pragma("unroll") for (int m = 0; m < 4; ++m) _Pragma("unroll") for (int n = 0; n < 2; ++n) _Pragma("unroll") for (int k = 0; k < 2; ++k) \
;         acc[ai][bj][m][n] = __builtin_amdgcn_mfma_f32_16x16x32_bf16(Bt[n][k], At[m][k], acc[ai][bj][m][n], 0, 0, 0); __builtin_amdgcn_s_setprio(0); } while (0)
; #define PG8_WAIT_V(n) asm volatile("s_waitcnt vmcnt(" #n ")" ::: "memory")
; #define PG8_WAIT_L(n) asm volatile("s_waitcnt lgkmcnt(" #n ")" ::: "memory")
; #define PG8_BAR __builtin_amdgcn_s_barrier()
; #define PG8_SCHED __builtin_amdgcn_sched_barrier(0)
; template <class Epi, class Sched, bool ALIGN_EPI = false, bool SP2 = false>
; __device__ __forceinline__ void gemm_phase(PG8_LAS unsigned char* lds, const Gemm g, const Sched& S, const Epi& E) {
;     ...
;             PG8_LDB(B0, 0, 0); PG8_LDB(B1, 0, 1); PG8_SCHED; PG8_LDA(At, 0, 0); PG8_STAGE(PG8_SA(1, 1), a1 + hstep, voffA);
;             PG8_WAIT_V(8); PG8_WAIT_L(0); PG8_BAR; PG8_MMA(0, 0, At, B0); PG8_MMA(0, 1, At, B1); PG8_BAR; PG8_SCHED;
;             PG8_LDA(At, 0, 1); PG8_STAGE(PG8_SB(0, 0), b2, voffB); PG8_STAGE(PG8_SB(0, 1), b2 + hstep, voffB); PG8_STAGE(PG8_SA(0, 0), a2, voffA);
;             PG8_WAIT_V(8); PG8_WAIT_L(0); PG8_BAR; PG8_MMA(1, 0, At, B0); PG8_MMA(1, 1, At, B1); PG8_BAR; PG8_SCHED;
.LBB0_56:
	s_add_i32 s2, s34, 2
	s_add_u32 s35, s28, s30
	s_addc_u32 s62, s29, s31
	s_add_u32 s63, s35, 0x100
	s_addc_u32 s35, s62, 0
	s_add_u32 s62, s60, s30
	s_addc_u32 s64, s61, s31
	s_add_i32 s65, 0, 0x10000
	s_cmp_eq_u32 s48, s34
	s_cselect_b32 s35, s1, s35
	s_cselect_b32 s34, s0, s63
	v_add_u32_e32 v0, s65, v188
	s_cselect_b32 s63, s27, s64
	s_cselect_b32 s62, s26, s62
	s_add_i32 s64, 0, 0x14000
	ds_read_b128 v[132:135], v0
	ds_read_b128 v[136:139], v0 offset:1024
	ds_read_b128 v[140:143], v0 offset:2048
	ds_read_b128 v[144:147], v0 offset:3072
	v_add_u32_e32 v0, s64, v188
	ds_read_b128 v[148:151], v0
	ds_read_b128 v[152:155], v0 offset:1024
	ds_read_b128 v[156:159], v0 offset:2048
	ds_read_b128 v[160:163], v0 offset:3072
	v_lshl_add_u64 v[2:3], v[204:205], 0, s[30:31]
	s_add_i32 m0, s43, 0xc000
	ds_read_b128 v[164:167], v235
	ds_read_b128 v[168:171], v235 offset:1024
	ds_read_b128 v[172:175], v235 offset:2048
	ds_read_b128 v[176:179], v235 offset:3072
	ds_read_b128 v[180:183], v235 offset:4096
	ds_read_b128 v[184:187], v235 offset:5120
	ds_read_b128 v[236:239], v235 offset:6144
	ds_read_b128 v[240:243], v235 offset:7168
	global_load_lds_dwordx4 v[2:3], off
	v_lshl_add_u64 v[2:3], v[206:207], 0, s[30:31]
	s_add_i32 m0, s43, 0xe000
	s_nop 0
	global_load_lds_dwordx4 v[2:3], off
	s_waitcnt vmcnt(8)
	s_waitcnt lgkmcnt(0)
	s_setprio 1
	s_barrier
	v_mfma_f32_16x16x32_bf16 v[116:119], v[132:135], v[164:167], v[116:119]
	v_mfma_f32_16x16x32_bf16 v[116:119], v[136:139], v[168:171], v[116:119]
	v_mfma_f32_16x16x32_bf16 v[120:123], v[140:143], v[164:167], v[120:123]
	v_mfma_f32_16x16x32_bf16 v[120:123], v[144:147], v[168:171], v[120:123]
	v_mfma_f32_16x16x32_bf16 v[104:107], v[140:143], v[172:175], v[104:107]
	v_mfma_f32_16x16x32_bf16 v[104:107], v[144:147], v[176:179], v[104:107]
	v_mfma_f32_16x16x32_bf16 v[100:103], v[132:135], v[172:175], v[100:103]
	v_mfma_f32_16x16x32_bf16 v[100:103], v[136:139], v[176:179], v[100:103]
	v_mfma_f32_16x16x32_bf16 v[76:79], v[132:135], v[180:183], v[76:79]
	v_mfma_f32_16x16x32_bf16 v[76:79], v[136:139], v[184:187], v[76:79]
	v_mfma_f32_16x16x32_bf16 v[80:83], v[140:143], v[180:183], v[80:83]
	v_mfma_f32_16x16x32_bf16 v[80:83], v[144:147], v[184:187], v[80:83]
	v_mfma_f32_16x16x32_bf16 v[48:51], v[140:143], v[236:239], v[48:51]
	v_mfma_f32_16x16x32_bf16 v[48:51], v[144:147], v[240:243], v[48:51]
	v_mfma_f32_16x16x32_bf16 v[44:47], v[132:135], v[236:239], v[44:47]
	v_mfma_f32_16x16x32_bf16 v[44:47], v[136:139], v[240:243], v[44:47]
	v_mfma_f32_16x16x32_bf16 v[124:127], v[148:151], v[164:167], v[124:127]
	v_mfma_f32_16x16x32_bf16 v[124:127], v[152:155], v[168:171], v[124:127]
	v_mfma_f32_16x16x32_bf16 v[128:131], v[156:159], v[164:167], v[128:131]
	v_mfma_f32_16x16x32_bf16 v[128:131], v[160:163], v[168:171], v[128:131]
	v_mfma_f32_16x16x32_bf16 v[112:115], v[156:159], v[172:175], v[112:115]
	v_mfma_f32_16x16x32_bf16 v[112:115], v[160:163], v[176:179], v[112:115]
	v_mfma_f32_16x16x32_bf16 v[108:111], v[148:151], v[172:175], v[108:111]
	v_mfma_f32_16x16x32_bf16 v[108:111], v[152:155], v[176:179], v[108:111]
	v_mfma_f32_16x16x32_bf16 v[92:95], v[148:151], v[180:183], v[92:95]
	v_mfma_f32_16x16x32_bf16 v[92:95], v[152:155], v[184:187], v[92:95]
	v_mfma_f32_16x16x32_bf16 v[96:99], v[156:159], v[180:183], v[96:99]
	v_mfma_f32_16x16x32_bf16 v[96:99], v[160:163], v[184:187], v[96:99]
	v_mfma_f32_16x16x32_bf16 v[72:75], v[156:159], v[236:239], v[72:75]
	v_mfma_f32_16x16x32_bf16 v[72:75], v[160:163], v[240:243], v[72:75]
	v_mfma_f32_16x16x32_bf16 v[68:71], v[148:151], v[236:239], v[68:71]
	v_mfma_f32_16x16x32_bf16 v[68:71], v[152:155], v[240:243], v[68:71]
	s_barrier
	s_setprio 0
	s_add_i32 s65, s65, s41
	v_lshl_add_u64 v[208:209], s[62:63], 0, v[192:193]
	s_mov_b32 m0, s65
	ds_read_b128 v[164:167], v235 offset:16384
	ds_read_b128 v[168:171], v235 offset:17408
	ds_read_b128 v[172:175], v235 offset:18432
	ds_read_b128 v[176:179], v235 offset:19456
	ds_read_b128 v[180:183], v235 offset:20480
	ds_read_b128 v[184:187], v235 offset:21504
	ds_read_b128 v[236:239], v235 offset:22528
	ds_read_b128 v[240:243], v235 offset:23552
	global_load_lds_dwordx4 v[208:209], off
	s_add_i32 m0, s65, 0x2000
	v_lshl_add_u64 v[244:245], s[62:63], 0, v[196:197]
	s_add_u32 s62, s62, s16
	s_addc_u32 s63, s63, 0
	s_add_i32 s64, s64, s41
	global_load_lds_dwordx4 v[244:245], off
	v_lshl_add_u64 v[246:247], s[62:63], 0, v[192:193]
	s_mov_b32 m0, s64
	v_lshl_add_u64 v[248:249], s[62:63], 0, v[196:197]
	global_load_lds_dwordx4 v[246:247], off
	s_add_i32 m0, s64, 0x2000
	v_lshl_add_u64 v[250:251], s[34:35], 0, v[190:191]
	global_load_lds_dwordx4 v[248:249], off
	s_mov_b32 m0, s43
	v_lshl_add_u64 v[212:213], s[34:35], 0, v[194:195]
	global_load_lds_dwordx4 v[250:251], off
	s_mov_b32 m0, s44
	s_nop 0
	global_load_lds_dwordx4 v[212:213], off
	s_waitcnt vmcnt(8)
	s_waitcnt lgkmcnt(0)
	s_setprio 1
	s_barrier
; #define PG8_STAGE(bufoff, gbase, voff) do { _Pragma("unroll") for (int _i = 0; _i < 2; ++_i) \
;         __builtin_amdgcn_global_load_lds((const unsigned*)((const char*)(gbase) + (voff)[_i]), (PG8_LAS unsigned*)(lds + (bufoff) + ldsw + _i * 8192), 16, 0, 0); } while (0)
; #define PG8_LDA(dst, b, h) do { _Pragma("unroll") for (int m = 0; m < 4; ++m) _Pragma("unroll") for (int k = 0; k < 2; ++k) dst[m][k] = *(const PG8_LAS bf16x8*)(lds + PG8_SA(b, h) + aoff + m * 2048 + k * 1024); } while (0)
; #define PG8_LDB(dst, b, h) do { _Pragma("unroll") for (int n = 0; n < 2; ++n) _Pragma("unroll") for (int k = 0; k < 2; ++k) dst[n][k] = *(const PG8_LAS bf16x8*)(lds + PG8_SB(b, h) + boff + n * 2048 + k * 1024); } while (0)
; #define PG8_MMA(ai, bj, At, Bt) do { __builtin_amdgcn_s_setprio(1); _Pragma("unroll") for (int m = 0; m < 4; ++m) _Pragma("unroll") for (int n = 0; n < 2; ++n) _Pragma("unroll") for (int k = 0; k < 2; ++k) \
;         acc[ai][bj][m][n] = __builtin_amdgcn_mfma_f32_16x16x32_bf16(Bt[n][k], At[m][k], acc[ai][bj][m][n], 0, 0, 0); __builtin_amdgcn_s_setprio(0); } while (0)
; #define PG8_WAIT_V(n) asm volatile("s_waitcnt vmcnt(" #n ")" ::: "memory")
; #define PG8_WAIT_L(n) asm volatile("s_waitcnt lgkmcnt(" #n ")" ::: "memory")
; #define PG8_BAR __builtin_amdgcn_s_barrier()
; #define PG8_SCHED __builtin_amdgcn_sched_barrier(0)
; template <class Epi, class Sched, bool ALIGN_EPI = false, bool SP2 = false>
; __device__ __forceinline__ void gemm_phase(PG8_LAS unsigned char* lds, const Gemm g, const Sched& S, const Epi& E) {
;     ...
;             PG8_WAIT_V(8); PG8_WAIT_L(0); PG8_BAR; PG8_MMA(1, 0, At, B0); PG8_MMA(1, 1, At, B1); PG8_BAR; PG8_SCHED;
;             PG8_LDB(B0, 1, 0); PG8_LDB(B1, 1, 1); PG8_SCHED; PG8_LDA(At, 1, 0); PG8_STAGE(PG8_SA(0, 1), a2 + hstep, voffA);
;             PG8_WAIT_V(8); PG8_WAIT_L(0); PG8_BAR; PG8_MMA(0, 0, At, B0); PG8_MMA(0, 1, At, B1); PG8_BAR; PG8_SCHED;
	v_mfma_f32_16x16x32_bf16 v[60:63], v[132:135], v[164:167], v[60:63]
	v_mfma_f32_16x16x32_bf16 v[60:63], v[136:139], v[168:171], v[60:63]
	v_mfma_f32_16x16x32_bf16 v[64:67], v[140:143], v[164:167], v[64:67]
	v_mfma_f32_16x16x32_bf16 v[64:67], v[144:147], v[168:171], v[64:67]
	v_mfma_f32_16x16x32_bf16 v[40:43], v[140:143], v[172:175], v[40:43]
	v_mfma_f32_16x16x32_bf16 v[40:43], v[144:147], v[176:179], v[40:43]
	v_mfma_f32_16x16x32_bf16 v[36:39], v[132:135], v[172:175], v[36:39]
	v_mfma_f32_16x16x32_bf16 v[36:39], v[136:139], v[176:179], v[36:39]
	v_mfma_f32_16x16x32_bf16 v[20:23], v[132:135], v[180:183], v[20:23]
	v_mfma_f32_16x16x32_bf16 v[20:23], v[136:139], v[184:187], v[20:23]
	v_mfma_f32_16x16x32_bf16 v[24:27], v[140:143], v[180:183], v[24:27]
	v_mfma_f32_16x16x32_bf16 v[24:27], v[144:147], v[184:187], v[24:27]
	v_mfma_f32_16x16x32_bf16 v[2:5], v[132:135], v[236:239], v[4:7]
	v_mfma_f32_16x16x32_bf16 v[2:5], v[136:139], v[240:243], v[2:5]
	v_mfma_f32_16x16x32_bf16 v[6:9], v[140:143], v[236:239], v[8:11]
	v_mfma_f32_16x16x32_bf16 v[8:11], v[144:147], v[240:243], v[6:9]
	v_mfma_f32_16x16x32_bf16 v[84:87], v[148:151], v[164:167], v[84:87]
	v_mfma_f32_16x16x32_bf16 v[84:87], v[152:155], v[168:171], v[84:87]
	v_mfma_f32_16x16x32_bf16 v[88:91], v[156:159], v[164:167], v[88:91]
	v_mfma_f32_16x16x32_bf16 v[88:91], v[160:163], v[168:171], v[88:91]
	v_mfma_f32_16x16x32_bf16 v[56:59], v[156:159], v[172:175], v[56:59]
	v_mfma_f32_16x16x32_bf16 v[56:59], v[160:163], v[176:179], v[56:59]
	v_mfma_f32_16x16x32_bf16 v[52:55], v[148:151], v[172:175], v[52:55]
	v_mfma_f32_16x16x32_bf16 v[52:55], v[152:155], v[176:179], v[52:55]
	v_mfma_f32_16x16x32_bf16 v[28:31], v[148:151], v[180:183], v[28:31]
	v_mfma_f32_16x16x32_bf16 v[28:31], v[152:155], v[184:187], v[28:31]
	v_mfma_f32_16x16x32_bf16 v[32:35], v[156:159], v[180:183], v[32:35]
	v_mfma_f32_16x16x32_bf16 v[32:35], v[160:163], v[184:187], v[32:35]
	v_mfma_f32_16x16x32_bf16 v[16:19], v[156:159], v[236:239], v[16:19]
	v_mfma_f32_16x16x32_bf16 v[16:19], v[160:163], v[240:243], v[16:19]
	v_mfma_f32_16x16x32_bf16 v[12:15], v[148:151], v[236:239], v[12:15]
	v_mfma_f32_16x16x32_bf16 v[12:15], v[152:155], v[240:243], v[12:15]
	s_barrier
	s_setprio 0
	s_add_i32 s62, 0, 0x18000
	v_add_u32_e32 v0, s62, v188
	s_add_i32 s63, 0, 0x1c000
	ds_read_b128 v[132:135], v0
	ds_read_b128 v[136:139], v0 offset:1024
	ds_read_b128 v[140:143], v0 offset:2048
	ds_read_b128 v[144:147], v0 offset:3072
	v_add_u32_e32 v0, s63, v188
	ds_read_b128 v[148:151], v0
	ds_read_b128 v[152:155], v0 offset:1024
	ds_read_b128 v[156:159], v0 offset:2048
	ds_read_b128 v[160:163], v0 offset:3072
	s_add_u32 s34, s34, s16
	s_addc_u32 s35, s35, 0
	s_mov_b32 m0, s45
	v_lshl_add_u64 v[6:7], s[34:35], 0, v[190:191]
	ds_read_b128 v[164:167], v235 offset:32768
	ds_read_b128 v[168:171], v235 offset:33792
	ds_read_b128 v[172:175], v235 offset:34816
	ds_read_b128 v[176:179], v235 offset:35840
	ds_read_b128 v[180:183], v235 offset:36864
	ds_read_b128 v[184:187], v235 offset:37888
	ds_read_b128 v[236:239], v235 offset:38912
	ds_read_b128 v[240:243], v235 offset:39936
	global_load_lds_dwordx4 v[6:7], off
	v_lshl_add_u64 v[6:7], s[34:35], 0, v[194:195]
	s_mov_b32 m0, s46
	s_nop 0
	global_load_lds_dwordx4 v[6:7], off
	s_waitcnt vmcnt(8)
	s_waitcnt lgkmcnt(0)
	s_setprio 1
	s_barrier
	v_mfma_f32_16x16x32_bf16 v[116:119], v[132:135], v[164:167], v[116:119]
	v_mfma_f32_16x16x32_bf16 v[116:119], v[136:139], v[168:171], v[116:119]
	v_mfma_f32_16x16x32_bf16 v[120:123], v[140:143], v[164:167], v[120:123]
	v_mfma_f32_16x16x32_bf16 v[120:123], v[144:147], v[168:171], v[120:123]
	v_mfma_f32_16x16x32_bf16 v[104:107], v[140:143], v[172:175], v[104:107]
	v_mfma_f32_16x16x32_bf16 v[104:107], v[144:147], v[176:179], v[104:107]
	v_mfma_f32_16x16x32_bf16 v[100:103], v[132:135], v[172:175], v[100:103]
	v_mfma_f32_16x16x32_bf16 v[100:103], v[136:139], v[176:179], v[100:103]
	v_mfma_f32_16x16x32_bf16 v[76:79], v[132:135], v[180:183], v[76:79]
	v_mfma_f32_16x16x32_bf16 v[76:79], v[136:139], v[184:187], v[76:79]
	v_mfma_f32_16x16x32_bf16 v[80:83], v[140:143], v[180:183], v[80:83]
	v_mfma_f32_16x16x32_bf16 v[80:83], v[144:147], v[184:187], v[80:83]
	v_mfma_f32_16x16x32_bf16 v[48:51], v[140:143], v[236:239], v[48:51]
	v_mfma_f32_16x16x32_bf16 v[48:51], v[144:147], v[240:243], v[48:51]
	v_mfma_f32_16x16x32_bf16 v[44:47], v[132:135], v[236:239], v[44:47]
	v_mfma_f32_16x16x32_bf16 v[44:47], v[136:139], v[240:243], v[44:47]
	v_mfma_f32_16x16x32_bf16 v[124:127], v[148:151], v[164:167], v[124:127]
	v_mfma_f32_16x16x32_bf16 v[124:127], v[152:155], v[168:171], v[124:127]
	v_mfma_f32_16x16x32_bf16 v[128:131], v[156:159], v[164:167], v[128:131]
	v_mfma_f32_16x16x32_bf16 v[128:131], v[160:163], v[168:171], v[128:131]
	v_mfma_f32_16x16x32_bf16 v[112:115], v[156:159], v[172:175], v[112:115]
	v_mfma_f32_16x16x32_bf16 v[112:115], v[160:163], v[176:179], v[112:115]
	v_mfma_f32_16x16x32_bf16 v[108:111], v[148:151], v[172:175], v[108:111]
	v_mfma_f32_16x16x32_bf16 v[108:111], v[152:155], v[176:179], v[108:111]
	v_mfma_f32_16x16x32_bf16 v[92:95], v[148:151], v[180:183], v[92:95]
	v_mfma_f32_16x16x32_bf16 v[92:95], v[152:155], v[184:187], v[92:95]
	v_mfma_f32_16x16x32_bf16 v[96:99], v[156:159], v[180:183], v[96:99]
	v_mfma_f32_16x16x32_bf16 v[96:99], v[160:163], v[184:187], v[96:99]
	v_mfma_f32_16x16x32_bf16 v[72:75], v[156:159], v[236:239], v[72:75]
	v_mfma_f32_16x16x32_bf16 v[72:75], v[160:163], v[240:243], v[72:75]
	v_mfma_f32_16x16x32_bf16 v[68:71], v[148:151], v[236:239], v[68:71]
	v_mfma_f32_16x16x32_bf16 v[68:71], v[152:155], v[240:243], v[68:71]
	s_barrier
; #define PG8_STAGE(bufoff, gbase, voff) do { _Pragma("unroll") for (int _i = 0; _i < 2; ++_i) \
;         __builtin_amdgcn_global_load_lds((const unsigned*)((const char*)(gbase) + (voff)[_i]), (PG8_LAS unsigned*)(lds + (bufoff) + ldsw + _i * 8192), 16, 0, 0); } while (0)
; #define PG8_LDA(dst, b, h) do { _Pragma("unroll") for (int m = 0; m < 4; ++m) _Pragma("unroll") for (int k = 0; k < 2; ++k) dst[m][k] = *(const PG8_LAS bf16x8*)(lds + PG8_SA(b, h) + aoff + m * 2048 + k * 1024); } while (0)
; #define PG8_MMA(ai, bj, At, Bt) do { __builtin_amdgcn_s_setprio(1); _Pragma("unroll") for (int m = 0; m < 4; ++m) _Pragma("unroll") for (int n = 0; n < 2; ++n) _Pragma("unroll") for (int k = 0; k < 2; ++k) \
;         acc[ai][bj][m][n] = __builtin_amdgcn_mfma_f32_16x16x32_bf16(Bt[n][k], At[m][k], acc[ai][bj][m][n], 0, 0, 0); __builtin_amdgcn_s_setprio(0); } while (0)
; #define PG8_WAIT_V(n) asm volatile("s_waitcnt vmcnt(" #n ")" ::: "memory")
; #define PG8_WAIT_L(n) asm volatile("s_waitcnt lgkmcnt(" #n ")" ::: "memory")
; #define PG8_BAR __builtin_amdgcn_s_barrier()
; #define PG8_SCHED __builtin_amdgcn_sched_barrier(0)
; template <class Epi, class Sched, bool ALIGN_EPI = false, bool SP2 = false>
; __device__ __forceinline__ void gemm_phase(PG8_LAS unsigned char* lds, const Gemm g, const Sched& S, const Epi& E) {
;     ...
;         for (int t = 0; t < nt; t += 2) {
;             if constexpr (Epi::KHOOK) { if (E.khook_at(t)) E.khook(acc, cur, t, wr, wc, fr, fq); }
;             const bool last = (t == nt - 2);
;             const char* a1 = cA + (size_t)(t + 1) * kstep;
;             const char* a2 = last ? nA : cA + (size_t)(t + 2) * kstep; const char* b2 = last ? nB : cB + (size_t)(t + 2) * kstep;
;     ...
;             PG8_LDA(At, 1, 1); PG8_STAGE(PG8_SB(1, 0), b3, voffB); PG8_STAGE(PG8_SB(1, 1), b3 + hstep, voffB); PG8_STAGE(PG8_SA(1, 0), a3, voffA);
;             PG8_WAIT_V(8); PG8_WAIT_L(0); PG8_BAR; PG8_MMA(1, 0, At, B0); PG8_MMA(1, 1, At, B1); PG8_BAR; PG8_SCHED;
	s_setprio 0
	s_add_i32 s34, s62, s41
	v_lshl_add_u64 v[6:7], v[208:209], 0, s[92:93]
	s_mov_b32 m0, s34
	ds_read_b128 v[164:167], v235 offset:49152
	ds_read_b128 v[168:171], v235 offset:50176
	ds_read_b128 v[172:175], v235 offset:51200
	ds_read_b128 v[176:179], v235 offset:52224
	ds_read_b128 v[180:183], v235 offset:53248
	ds_read_b128 v[184:187], v235 offset:54272
	ds_read_b128 v[236:239], v235 offset:55296
	ds_read_b128 v[240:243], v235 offset:56320
	global_load_lds_dwordx4 v[6:7], off
	v_lshl_add_u64 v[6:7], v[244:245], 0, s[92:93]
	s_add_i32 m0, s34, 0x2000
	s_add_i32 s34, s63, s41
	global_load_lds_dwordx4 v[6:7], off
	v_lshl_add_u64 v[6:7], v[246:247], 0, s[92:93]
	s_mov_b32 m0, s34
	s_nop 0
	global_load_lds_dwordx4 v[6:7], off
	v_lshl_add_u64 v[6:7], v[248:249], 0, s[92:93]
	s_add_i32 m0, s34, 0x2000
	s_nop 0
	global_load_lds_dwordx4 v[6:7], off
	v_lshl_add_u64 v[6:7], v[250:251], 0, s[92:93]
	s_mov_b32 m0, s51
	s_nop 0
	global_load_lds_dwordx4 v[6:7], off
	v_lshl_add_u64 v[6:7], v[212:213], 0, s[92:93]
	s_mov_b32 m0, s52
	s_nop 0
	global_load_lds_dwordx4 v[6:7], off
	s_waitcnt vmcnt(8)
	s_waitcnt lgkmcnt(0)
	s_setprio 1
	s_barrier
	v_mfma_f32_16x16x32_bf16 v[60:63], v[132:135], v[164:167], v[60:63]
	v_mfma_f32_16x16x32_bf16 v[60:63], v[136:139], v[168:171], v[60:63]
	s_add_u32 s30, s30, 0x100
	s_addc_u32 s31, s31, 0
	s_cmp_ge_u32 s2, s47
	v_mfma_f32_16x16x32_bf16 v[64:67], v[140:143], v[164:167], v[64:67]
	v_mfma_f32_16x16x32_bf16 v[64:67], v[144:147], v[168:171], v[64:67]
	v_mfma_f32_16x16x32_bf16 v[40:43], v[140:143], v[172:175], v[40:43]
	v_mfma_f32_16x16x32_bf16 v[40:43], v[144:147], v[176:179], v[40:43]
	v_mfma_f32_16x16x32_bf16 v[36:39], v[132:135], v[172:175], v[36:39]
	v_mfma_f32_16x16x32_bf16 v[36:39], v[136:139], v[176:179], v[36:39]
	v_mfma_f32_16x16x32_bf16 v[20:23], v[132:135], v[180:183], v[20:23]
	v_mfma_f32_16x16x32_bf16 v[20:23], v[136:139], v[184:187], v[20:23]
	v_mfma_f32_16x16x32_bf16 v[24:27], v[140:143], v[180:183], v[24:27]
	v_mfma_f32_16x16x32_bf16 v[24:27], v[144:147], v[184:187], v[24:27]
	v_mfma_f32_16x16x32_bf16 v[8:11], v[140:143], v[236:239], v[8:11]
	v_mfma_f32_16x16x32_bf16 v[8:11], v[144:147], v[240:243], v[8:11]
	v_mfma_f32_16x16x32_bf16 v[2:5], v[132:135], v[236:239], v[2:5]
	v_mfma_f32_16x16x32_bf16 v[4:7], v[136:139], v[240:243], v[2:5]
	v_mfma_f32_16x16x32_bf16 v[84:87], v[148:151], v[164:167], v[84:87]
	v_mfma_f32_16x16x32_bf16 v[84:87], v[152:155], v[168:171], v[84:87]
	v_mfma_f32_16x16x32_bf16 v[88:91], v[156:159], v[164:167], v[88:91]
	v_mfma_f32_16x16x32_bf16 v[88:91], v[160:163], v[168:171], v[88:91]
	v_mfma_f32_16x16x32_bf16 v[56:59], v[156:159], v[172:175], v[56:59]
	v_mfma_f32_16x16x32_bf16 v[56:59], v[160:163], v[176:179], v[56:59]
	v_mfma_f32_16x16x32_bf16 v[52:55], v[148:151], v[172:175], v[52:55]
	v_mfma_f32_16x16x32_bf16 v[52:55], v[152:155], v[176:179], v[52:55]
	v_mfma_f32_16x16x32_bf16 v[28:31], v[148:151], v[180:183], v[28:31]
	v_mfma_f32_16x16x32_bf16 v[28:31], v[152:155], v[184:187], v[28:31]
	v_mfma_f32_16x16x32_bf16 v[32:35], v[156:159], v[180:183], v[32:35]
	v_mfma_f32_16x16x32_bf16 v[32:35], v[160:163], v[184:187], v[32:35]
	v_mfma_f32_16x16x32_bf16 v[16:19], v[156:159], v[236:239], v[16:19]
	v_mfma_f32_16x16x32_bf16 v[16:19], v[160:163], v[240:243], v[16:19]
	v_mfma_f32_16x16x32_bf16 v[12:15], v[148:151], v[236:239], v[12:15]
	v_mfma_f32_16x16x32_bf16 v[12:15], v[152:155], v[240:243], v[12:15]
	s_barrier
	s_setprio 0
	s_cbranch_scc1 .LBB0_58
	s_mov_b32 s34, s2
	s_branch .LBB0_54
